# GEMM glds saddr addressing, ATTD PV ds_read pipelining + tile prefetch, NORM prologue loads de-serialized
# speedup vs baseline: 1.0090x; 1.0090x over previous
.LBB0_174:
	s_cmp_lt_u32 s86, 31
	s_cselect_b64 s[14:15], -1, 0
	s_and_b64 s[14:15], s[28:29], s[14:15]
	v_cndmask_b32_e64 v96, 0, 1, s[14:15]
	v_cmp_ne_u32_e64 s[42:43], 1, v96
	s_andn2_b64 vcc, exec, s[14:15]
	s_mov_b64 s[14:15], -1
	s_cbranch_vccz .LBB0_179
	v_lshl_add_u64 v[98:99], v[218:219], 0, s[30:31]
	global_load_dwordx4 v[132:135], v[98:99], off
	global_load_dwordx4 v[136:139], v[98:99], off offset:128
	v_lshl_add_u64 v[98:99], v[214:215], 0, s[30:31]
	v_lshl_add_u64 v[144:145], v[212:213], 0, s[30:31]
	global_load_dwordx4 v[140:143], v[98:99], off
	s_nop 0
	global_load_dwordx4 v[144:147], v[144:145], off
	s_add_u32 s6, s30, s87
	s_addc_u32 s7, s31, 0
	v_lshl_add_u64 v[116:117], v[218:219], 0, s[6:7]
	v_lshl_add_u64 v[118:119], v[214:215], 0, s[6:7]
	global_load_dwordx4 v[100:103], v[116:117], off
	global_load_dwordx4 v[104:107], v[116:117], off offset:128
	v_lshl_add_u64 v[116:117], v[212:213], 0, s[6:7]
	global_load_dwordx4 v[108:111], v[118:119], off
	s_nop 0
	global_load_dwordx4 v[112:115], v[116:117], off
	s_cbranch_execz .LBB0_180

; DI void phase_attd(ArgsP AP, LAS unsigned char* lds, int rep) {
;     ...
;             if (pend) { AD_PV(pq0, pq1, pq2, pq3, pvs); pend = false; }
.LBB0_177:
	s_mul_i32 s2, s36, 0x4800
	v_add_u32_e32 v96, s2, v233
	ds_read_b64_tr_b16 v[80:81], v96 offset:36864
	ds_read_b64_tr_b16 v[82:83], v96 offset:39168
	ds_read_b64_tr_b16 v[84:85], v96 offset:41472
	ds_read_b64_tr_b16 v[86:87], v96 offset:43776
	ds_read_b64_tr_b16 v[88:89], v96 offset:46080
	ds_read_b64_tr_b16 v[90:91], v96 offset:48384
	ds_read_b64_tr_b16 v[92:93], v96 offset:50688
	ds_read_b64_tr_b16 v[94:95], v96 offset:52992
	s_waitcnt lgkmcnt(6)
	v_mfma_f32_32x32x16_bf16 v[48:63], v[80:83], v[76:79], v[48:63]
	ds_read_b64_tr_b16 v[80:81], v96 offset:36928
	ds_read_b64_tr_b16 v[82:83], v96 offset:39232
	s_waitcnt lgkmcnt(6)
	v_mfma_f32_32x32x16_bf16 v[48:63], v[84:87], v[72:75], v[48:63]
	ds_read_b64_tr_b16 v[84:85], v96 offset:41536
	ds_read_b64_tr_b16 v[86:87], v96 offset:43840
	s_waitcnt lgkmcnt(6)
	v_mfma_f32_32x32x16_bf16 v[48:63], v[88:91], v[68:71], v[48:63]
	ds_read_b64_tr_b16 v[88:89], v96 offset:46144
	ds_read_b64_tr_b16 v[90:91], v96 offset:48448
	s_waitcnt lgkmcnt(6)
	v_mfma_f32_32x32x16_bf16 v[48:63], v[92:95], v[64:67], v[48:63]
	ds_read_b64_tr_b16 v[92:93], v96 offset:50752
	ds_read_b64_tr_b16 v[94:95], v96 offset:53056
	s_waitcnt lgkmcnt(6)
	v_mfma_f32_32x32x16_bf16 v[32:47], v[80:83], v[76:79], v[32:47]
	ds_read_b64_tr_b16 v[80:81], v96 offset:36992
	ds_read_b64_tr_b16 v[82:83], v96 offset:39296
	s_waitcnt lgkmcnt(6)
	v_mfma_f32_32x32x16_bf16 v[32:47], v[84:87], v[72:75], v[32:47]
	ds_read_b64_tr_b16 v[84:85], v96 offset:41600
	ds_read_b64_tr_b16 v[86:87], v96 offset:43904
	s_waitcnt lgkmcnt(6)
	v_mfma_f32_32x32x16_bf16 v[32:47], v[88:91], v[68:71], v[32:47]
	ds_read_b64_tr_b16 v[88:89], v96 offset:46208
	ds_read_b64_tr_b16 v[90:91], v96 offset:48512
	s_waitcnt lgkmcnt(6)
	v_mfma_f32_32x32x16_bf16 v[32:47], v[92:95], v[64:67], v[32:47]
	ds_read_b64_tr_b16 v[92:93], v96 offset:50816
	ds_read_b64_tr_b16 v[94:95], v96 offset:53120
	s_waitcnt lgkmcnt(6)
	v_mfma_f32_32x32x16_bf16 v[16:31], v[80:83], v[76:79], v[16:31]
	ds_read_b64_tr_b16 v[80:81], v96 offset:37056
	ds_read_b64_tr_b16 v[82:83], v96 offset:39360
	s_waitcnt lgkmcnt(6)
	v_mfma_f32_32x32x16_bf16 v[16:31], v[84:87], v[72:75], v[16:31]
	ds_read_b64_tr_b16 v[84:85], v96 offset:41664
	ds_read_b64_tr_b16 v[86:87], v96 offset:43968
	s_waitcnt lgkmcnt(6)
	v_mfma_f32_32x32x16_bf16 v[16:31], v[88:91], v[68:71], v[16:31]
	ds_read_b64_tr_b16 v[88:89], v96 offset:46272
	ds_read_b64_tr_b16 v[90:91], v96 offset:48576
	s_waitcnt lgkmcnt(6)
	v_mfma_f32_32x32x16_bf16 v[16:31], v[92:95], v[64:67], v[16:31]
	ds_read_b64_tr_b16 v[92:93], v96 offset:50880
	ds_read_b64_tr_b16 v[94:95], v96 offset:53184
	s_waitcnt lgkmcnt(6)
	v_mfma_f32_32x32x16_bf16 v[0:15], v[80:83], v[76:79], v[0:15]
	s_waitcnt lgkmcnt(4)
	v_mfma_f32_32x32x16_bf16 v[0:15], v[84:87], v[72:75], v[0:15]
	s_waitcnt lgkmcnt(2)
	v_mfma_f32_32x32x16_bf16 v[0:15], v[88:91], v[68:71], v[0:15]
	s_waitcnt lgkmcnt(0)
	v_mfma_f32_32x32x16_bf16 v[0:15], v[92:95], v[64:67], v[0:15]
	s_and_b32 s14, s86, 1
	s_cmp_ge_u32 s88, s84
	s_mov_b64 s[2:3], 0
	s_cbranch_scc0 .LBB0_182

; DI float fexp2(float x) { return __builtin_amdgcn_exp2f(x); }
; DI void phase_attd(ArgsP AP, LAS unsigned char* lds, int rep) {
;     ...
;                 const float mnew = fmaxf(mrun, mx), alpha = fexp2(mrun - mnew); mrun = mnew;
;                 float ps = 0.f;
; #pragma unroll
;                 for (int kb = 0; kb < 2; ++kb)
; #pragma unroll
;                     for (int i = 0; i < 16; ++i) { p[kb][i] = fexp2(p[kb][i] - mnew); ps += p[kb][i]; }
;                 lrun = lrun * alpha + ps;
;                 if (__any(alpha != 1.f)) {
; #pragma unroll
;                     for (int db = 0; db < 4; ++db) O[db] = O[db] * alpha; }
;                 pq0 = pack8(p[0], 0); pq1 = pack8(p[0], 1); pq2 = pack8(p[1], 0); pq3 = pack8(p[1], 1);
;                 if (comp == 0) AD_PV(pq0, pq1, pq2, pq3, vst); else { pend = true; pvs = vst; }
.LBB0_186:
	v_sub_f32_e32 v64, v64, v98
	v_exp_f32_e32 v99, v64
	v_sub_f32_e32 v64, v65, v98
	v_exp_f32_e32 v183, v64
	v_sub_f32_e32 v64, v66, v98
	v_exp_f32_e32 v185, v64
	v_sub_f32_e32 v64, v67, v98
	v_exp_f32_e32 v199, v64
	v_sub_f32_e32 v64, v68, v98
	v_exp_f32_e32 v201, v64
	v_sub_f32_e32 v64, v69, v98
	v_exp_f32_e32 v205, v64
	v_sub_f32_e32 v64, v70, v98
	v_exp_f32_e32 v207, v64
	v_sub_f32_e32 v64, v71, v98
	v_exp_f32_e32 v240, v64
	v_sub_f32_e32 v64, v72, v98
	v_exp_f32_e32 v241, v64
	v_sub_f32_e32 v64, v73, v98
	v_exp_f32_e32 v242, v64
	v_sub_f32_e32 v64, v74, v98
	v_exp_f32_e32 v243, v64
	v_sub_f32_e32 v64, v75, v98
	v_exp_f32_e32 v244, v64
	v_sub_f32_e32 v64, v76, v98
	v_exp_f32_e32 v245, v64
	v_sub_f32_e32 v64, v77, v98
	v_exp_f32_e32 v246, v64
	v_sub_f32_e32 v64, v78, v98
	v_sub_f32_e32 v80, v80, v98
	v_sub_f32_e32 v81, v81, v98
	v_sub_f32_e32 v82, v82, v98
	v_sub_f32_e32 v83, v83, v98
	v_sub_f32_e32 v84, v84, v98
	v_sub_f32_e32 v85, v85, v98
	v_sub_f32_e32 v86, v86, v98
	v_sub_f32_e32 v87, v87, v98
	v_sub_f32_e32 v88, v88, v98
	v_sub_f32_e32 v89, v89, v98
	v_sub_f32_e32 v90, v90, v98
	v_sub_f32_e32 v91, v91, v98
	v_sub_f32_e32 v92, v92, v98
	v_sub_f32_e32 v93, v93, v98
	v_sub_f32_e32 v94, v94, v98
	v_sub_f32_e32 v95, v95, v98
	v_exp_f32_e32 v247, v64
	v_sub_f32_e32 v64, v79, v98
	v_exp_f32_e32 v80, v80
	v_exp_f32_e32 v81, v81
	v_exp_f32_e32 v82, v82
	v_exp_f32_e32 v83, v83
	v_exp_f32_e32 v84, v84
	v_exp_f32_e32 v85, v85
	v_exp_f32_e32 v86, v86
	v_exp_f32_e32 v87, v87
	v_exp_f32_e32 v88, v88
	v_exp_f32_e32 v89, v89
	v_exp_f32_e32 v90, v90
	v_exp_f32_e32 v91, v91
	v_exp_f32_e32 v92, v92
	v_exp_f32_e32 v93, v93
	v_exp_f32_e32 v94, v94
	v_exp_f32_e32 v95, v95
	v_exp_f32_e32 v248, v64
	v_cvt_pk_bf16_f32 v76, v80, v81
	v_cvt_pk_bf16_f32 v77, v82, v83
	v_cvt_pk_bf16_f32 v78, v84, v85
	v_cvt_pk_bf16_f32 v79, v86, v87
	v_cvt_pk_bf16_f32 v72, v88, v89
	v_cvt_pk_bf16_f32 v73, v90, v91
	v_cvt_pk_bf16_f32 v74, v92, v93
	v_cvt_pk_bf16_f32 v75, v94, v95
	v_cvt_pk_bf16_f32 v68, v99, v183
	v_cvt_pk_bf16_f32 v69, v185, v199
	v_cvt_pk_bf16_f32 v70, v201, v205
	v_cvt_pk_bf16_f32 v71, v207, v240
	v_cvt_pk_bf16_f32 v64, v241, v242
	v_cvt_pk_bf16_f32 v65, v243, v244
	v_cvt_pk_bf16_f32 v66, v245, v246
	v_cvt_pk_bf16_f32 v67, v247, v248
	v_add_f32_e32 v80, 0, v80
	v_add_f32_e32 v80, v81, v80
	v_add_f32_e32 v80, v82, v80
	v_add_f32_e32 v80, v83, v80
	v_add_f32_e32 v80, v84, v80
	v_add_f32_e32 v80, v85, v80
	v_add_f32_e32 v80, v86, v80
	v_add_f32_e32 v80, v87, v80
	v_add_f32_e32 v80, v88, v80
	v_add_f32_e32 v80, v89, v80
	v_add_f32_e32 v80, v90, v80
	v_add_f32_e32 v80, v91, v80
	v_add_f32_e32 v80, v92, v80
	v_add_f32_e32 v80, v93, v80
	v_add_f32_e32 v80, v94, v80
	v_add_f32_e32 v80, v95, v80
	s_andn2_b64 vcc, exec, s[22:23]
	s_mov_b64 s[2:3], -1
	s_cbranch_vccnz .LBB0_188
	s_mulk_i32 s89, 0x4800
	v_add_u32_e32 v167, s89, v233
	ds_read_b64_tr_b16 v[228:229], v167 offset:36864
	ds_read_b64_tr_b16 v[230:231], v167 offset:39168
	ds_read_b64_tr_b16 v[84:85], v167 offset:41472
	ds_read_b64_tr_b16 v[86:87], v167 offset:43776
	ds_read_b64_tr_b16 v[88:89], v167 offset:46080
	ds_read_b64_tr_b16 v[90:91], v167 offset:48384
	ds_read_b64_tr_b16 v[92:93], v167 offset:50688
	ds_read_b64_tr_b16 v[94:95], v167 offset:52992
	s_mov_b64 s[2:3], 0
	v_add_f32_e32 v80, v99, v80
	v_add_f32_e32 v80, v183, v80
	v_add_f32_e32 v80, v185, v80
	v_add_f32_e32 v80, v199, v80
	v_add_f32_e32 v80, v201, v80
	v_add_f32_e32 v80, v205, v80
	v_add_f32_e32 v80, v207, v80
	v_add_f32_e32 v80, v240, v80
	v_add_f32_e32 v80, v241, v80
	v_add_f32_e32 v80, v242, v80
	v_add_f32_e32 v80, v243, v80
	v_add_f32_e32 v80, v244, v80
	v_add_f32_e32 v80, v245, v80
	v_add_f32_e32 v80, v246, v80
	v_add_f32_e32 v80, v247, v80
	v_add_f32_e32 v80, v248, v80
	v_fmac_f32_e32 v80, v171, v96
	v_mov_b32_e32 v171, v80
	s_waitcnt lgkmcnt(6)
	v_mfma_f32_32x32x16_bf16 v[48:63], v[228:231], v[76:79], v[48:63]
	ds_read_b64_tr_b16 v[228:229], v167 offset:36928
	ds_read_b64_tr_b16 v[230:231], v167 offset:39232
	s_waitcnt lgkmcnt(6)
	v_mfma_f32_32x32x16_bf16 v[48:63], v[84:87], v[72:75], v[48:63]
	ds_read_b64_tr_b16 v[84:85], v167 offset:41536
	ds_read_b64_tr_b16 v[86:87], v167 offset:43840
	s_waitcnt lgkmcnt(6)
	v_mfma_f32_32x32x16_bf16 v[48:63], v[88:91], v[68:71], v[48:63]
	ds_read_b64_tr_b16 v[88:89], v167 offset:46144
	ds_read_b64_tr_b16 v[90:91], v167 offset:48448
	s_waitcnt lgkmcnt(6)
	v_mfma_f32_32x32x16_bf16 v[48:63], v[92:95], v[64:67], v[48:63]
	ds_read_b64_tr_b16 v[92:93], v167 offset:50752
	ds_read_b64_tr_b16 v[94:95], v167 offset:53056
	s_waitcnt lgkmcnt(6)
	v_mfma_f32_32x32x16_bf16 v[32:47], v[228:231], v[76:79], v[32:47]
	ds_read_b64_tr_b16 v[228:229], v167 offset:36992
	ds_read_b64_tr_b16 v[230:231], v167 offset:39296
	s_waitcnt lgkmcnt(6)
	v_mfma_f32_32x32x16_bf16 v[32:47], v[84:87], v[72:75], v[32:47]
	ds_read_b64_tr_b16 v[84:85], v167 offset:41600
	ds_read_b64_tr_b16 v[86:87], v167 offset:43904
	s_waitcnt lgkmcnt(6)
	v_mfma_f32_32x32x16_bf16 v[32:47], v[88:91], v[68:71], v[32:47]
	ds_read_b64_tr_b16 v[88:89], v167 offset:46208
	ds_read_b64_tr_b16 v[90:91], v167 offset:48512
	s_waitcnt lgkmcnt(6)
	v_mfma_f32_32x32x16_bf16 v[32:47], v[92:95], v[64:67], v[32:47]
	ds_read_b64_tr_b16 v[92:93], v167 offset:50816
	ds_read_b64_tr_b16 v[94:95], v167 offset:53120
	s_waitcnt lgkmcnt(6)
	v_mfma_f32_32x32x16_bf16 v[16:31], v[228:231], v[76:79], v[16:31]
	ds_read_b64_tr_b16 v[228:229], v167 offset:37056
	ds_read_b64_tr_b16 v[230:231], v167 offset:39360
	s_waitcnt lgkmcnt(6)
	v_mfma_f32_32x32x16_bf16 v[16:31], v[84:87], v[72:75], v[16:31]
	ds_read_b64_tr_b16 v[84:85], v167 offset:41664
	ds_read_b64_tr_b16 v[86:87], v167 offset:43968
	s_waitcnt lgkmcnt(6)
	v_mfma_f32_32x32x16_bf16 v[16:31], v[88:91], v[68:71], v[16:31]
	ds_read_b64_tr_b16 v[88:89], v167 offset:46272
	ds_read_b64_tr_b16 v[90:91], v167 offset:48576
	s_waitcnt lgkmcnt(6)
	v_mfma_f32_32x32x16_bf16 v[16:31], v[92:95], v[64:67], v[16:31]
	ds_read_b64_tr_b16 v[92:93], v167 offset:50880
	ds_read_b64_tr_b16 v[94:95], v167 offset:53184
	s_waitcnt lgkmcnt(6)
	v_mfma_f32_32x32x16_bf16 v[0:15], v[228:231], v[76:79], v[0:15]
	s_waitcnt lgkmcnt(4)
	v_mfma_f32_32x32x16_bf16 v[0:15], v[84:87], v[72:75], v[0:15]
	s_waitcnt lgkmcnt(2)
	v_mfma_f32_32x32x16_bf16 v[0:15], v[88:91], v[68:71], v[0:15]
	s_waitcnt lgkmcnt(0)
	v_mfma_f32_32x32x16_bf16 v[0:15], v[92:95], v[64:67], v[0:15]
	s_branch .LBB0_189
; #define AD_STORE(sl, vs) do { AD_CVT(); *(LAS u32x4*)(lds + (sl) * AD_KST + krow * 144 + kch * 16) = st[0]; *(LAS u32x4*)(lds + (sl) * AD_KST + 9216 + krow * 144 + kch * 16) = st[1]; \
;             _Pragma("unroll") for (int i_ = 0; i_ < 2; ++i_) { const int idx_ = tid + 512 * i_; *(LAS u32x4*)(lds + AD_VOFF + (vs) * AD_VST + (idx_ >> 4) * 288 + (idx_ & 15) * 16) = st[2 + i_]; } } while (0)
; DI void phase_attd(ArgsP AP, LAS unsigned char* lds, int rep) {
;     ...
;                 lrun = lrun * alpha + ps;
;                 if (__any(alpha != 1.f)) {
; #pragma unroll
;                     for (int db = 0; db < 4; ++db) O[db] = O[db] * alpha; }
;                 pq0 = pack8(p[0], 0); pq1 = pack8(p[0], 1); pq2 = pack8(p[1], 0); pq3 = pack8(p[1], 1);
;                 if (comp == 0) AD_PV(pq0, pq1, pq2, pq3, vst); else { pend = true; pvs = vst; }
;             }
;             if (t + 1 < NT) AD_STORE(sl ^ 1, vnx);
;             __syncthreads();
;             vst = vnx; vnx = (vnx == 2) ? 0 : vnx + 1;
.LBB0_188:
	s_mov_b32 s36, s89
	v_add_f32_e32 v80, v99, v80
	v_add_f32_e32 v80, v183, v80
	v_add_f32_e32 v80, v185, v80
	v_add_f32_e32 v80, v199, v80
	v_add_f32_e32 v80, v201, v80
	v_add_f32_e32 v80, v205, v80
	v_add_f32_e32 v80, v207, v80
	v_add_f32_e32 v80, v240, v80
	v_add_f32_e32 v80, v241, v80
	v_add_f32_e32 v80, v242, v80
	v_add_f32_e32 v80, v243, v80
	v_add_f32_e32 v80, v244, v80
	v_add_f32_e32 v80, v245, v80
	v_add_f32_e32 v80, v246, v80
	v_add_f32_e32 v80, v247, v80
	v_add_f32_e32 v80, v248, v80
	v_fmac_f32_e32 v80, v171, v96
	v_mov_b32_e32 v171, v80
.LBB0_189:
	s_and_b64 vcc, exec, s[42:43]
	s_cbranch_vccnz .LBB0_191
.LBB0_190:
	s_waitcnt vmcnt(3)
	v_cvt_pk_bf16_f32 v132, v104, v105
	v_cvt_pk_bf16_f32 v133, v106, v107
	v_cvt_pk_bf16_f32 v134, v100, v101
	v_cvt_pk_bf16_f32 v135, v102, v103
	s_waitcnt vmcnt(2)
	v_cvt_pk_bf16_f32 v136, v112, v113
	v_cvt_pk_bf16_f32 v137, v114, v115
	v_cvt_pk_bf16_f32 v138, v108, v109
	v_cvt_pk_bf16_f32 v139, v110, v111
	s_waitcnt vmcnt(1)
	v_cvt_pk_bf16_f32 v140, v120, v121
	v_cvt_pk_bf16_f32 v141, v122, v123
	v_cvt_pk_bf16_f32 v142, v116, v117
	v_cvt_pk_bf16_f32 v143, v118, v119
	s_waitcnt vmcnt(0)
	v_cvt_pk_bf16_f32 v144, v128, v129
	v_cvt_pk_bf16_f32 v145, v130, v131
	v_cvt_pk_bf16_f32 v146, v124, v125
	v_cvt_pk_bf16_f32 v147, v126, v127
.LBB0_191:
	s_xor_b32 s6, s14, 1
	s_mulk_i32 s6, 0x4800
	v_add_u32_e32 v80, s6, v175
	s_add_i32 s6, s38, 1
	s_cmp_lg_u32 s38, 2
	s_cselect_b32 s15, s6, 0
	s_add_i32 s88, s88, 64
	s_add_u32 s34, s34, 0x40000
	s_addc_u32 s35, s35, 0
	s_mul_i32 s14, s38, 0x4800
	s_add_u32 s30, s30, s87
	s_waitcnt vmcnt(7)
	ds_write_b128 v80, v[132:135]
	s_waitcnt vmcnt(6)
	ds_write_b128 v80, v[136:139] offset:9216
	v_add_u32_e32 v80, s14, v181
	s_addc_u32 s31, s31, 0
	s_add_i32 s86, s86, 1
	v_add_u32_e32 v81, v80, v236
	v_add_u32_e32 v80, v80, v237
	s_cmp_eq_u32 s39, s88
	s_waitcnt vmcnt(5)
	ds_write_b128 v81, v[140:143] offset:36864
	s_waitcnt vmcnt(4)
	ds_write_b128 v80, v[144:147] offset:36864
	s_waitcnt lgkmcnt(0)
	s_barrier
	s_cbranch_scc1 .LBB0_195
	v_mov_b64_e32 v[92:93], v[144:145]
	v_mov_b64_e32 v[88:89], v[140:141]
	v_mov_b64_e32 v[84:85], v[136:137]
	v_mov_b64_e32 v[80:81], v[132:133]
	v_mov_b64_e32 v[94:95], v[146:147]
	v_mov_b64_e32 v[90:91], v[142:143]
	v_mov_b64_e32 v[86:87], v[138:139]
	v_mov_b64_e32 v[82:83], v[134:135]
	v_mov_b32_e32 v183, v98
	s_mov_b32 s89, s38
	s_mov_b32 s38, s15
	s_branch .LBB0_174

; DI void phase_attd(ArgsP AP, LAS unsigned char* lds, int rep) {
;     ...
;         if (pend) AD_PV(pq0, pq1, pq2, pq3, pvs);
.LBB0_195:
	s_waitcnt vmcnt(0)
	s_andn2_b64 vcc, exec, s[2:3]
	s_cbranch_vccnz .LBB0_197
	s_mul_i32 s2, s36, 0x4800
	v_add_u32_e32 v84, s2, v233
	ds_read_b64_tr_b16 v[80:81], v84 offset:36864
	ds_read_b64_tr_b16 v[82:83], v84 offset:39168
	s_waitcnt lgkmcnt(0)
	v_mfma_f32_32x32x16_bf16 v[48:63], v[80:83], v[76:79], v[48:63]
	ds_read_b64_tr_b16 v[80:81], v84 offset:41472
	ds_read_b64_tr_b16 v[82:83], v84 offset:43776
	s_waitcnt lgkmcnt(0)
	v_mfma_f32_32x32x16_bf16 v[48:63], v[80:83], v[72:75], v[48:63]
	ds_read_b64_tr_b16 v[80:81], v84 offset:46080
	ds_read_b64_tr_b16 v[82:83], v84 offset:48384
	s_waitcnt lgkmcnt(0)
	v_mfma_f32_32x32x16_bf16 v[48:63], v[80:83], v[68:71], v[48:63]
	ds_read_b64_tr_b16 v[80:81], v84 offset:50688
	ds_read_b64_tr_b16 v[82:83], v84 offset:52992
	s_waitcnt lgkmcnt(0)
	v_mfma_f32_32x32x16_bf16 v[48:63], v[80:83], v[64:67], v[48:63]
	ds_read_b64_tr_b16 v[80:81], v84 offset:36928
	ds_read_b64_tr_b16 v[82:83], v84 offset:39232
	s_waitcnt lgkmcnt(0)
	v_mfma_f32_32x32x16_bf16 v[32:47], v[80:83], v[76:79], v[32:47]
	ds_read_b64_tr_b16 v[80:81], v84 offset:41536
	ds_read_b64_tr_b16 v[82:83], v84 offset:43840
	s_waitcnt lgkmcnt(0)
	v_mfma_f32_32x32x16_bf16 v[32:47], v[80:83], v[72:75], v[32:47]
	ds_read_b64_tr_b16 v[80:81], v84 offset:46144
	ds_read_b64_tr_b16 v[82:83], v84 offset:48448
	s_waitcnt lgkmcnt(0)
	v_mfma_f32_32x32x16_bf16 v[32:47], v[80:83], v[68:71], v[32:47]
	ds_read_b64_tr_b16 v[80:81], v84 offset:50752
	ds_read_b64_tr_b16 v[82:83], v84 offset:53056
	s_waitcnt lgkmcnt(0)
	v_mfma_f32_32x32x16_bf16 v[32:47], v[80:83], v[64:67], v[32:47]
	ds_read_b64_tr_b16 v[80:81], v84 offset:36992
	ds_read_b64_tr_b16 v[82:83], v84 offset:39296
	s_waitcnt lgkmcnt(0)
	v_mfma_f32_32x32x16_bf16 v[16:31], v[80:83], v[76:79], v[16:31]
	ds_read_b64_tr_b16 v[80:81], v84 offset:41600
	ds_read_b64_tr_b16 v[82:83], v84 offset:43904
	s_waitcnt lgkmcnt(0)
	v_mfma_f32_32x32x16_bf16 v[16:31], v[80:83], v[72:75], v[16:31]
	ds_read_b64_tr_b16 v[80:81], v84 offset:46208
	ds_read_b64_tr_b16 v[82:83], v84 offset:48512
	s_waitcnt lgkmcnt(0)
	v_mfma_f32_32x32x16_bf16 v[16:31], v[80:83], v[68:71], v[16:31]
	ds_read_b64_tr_b16 v[80:81], v84 offset:50816
	ds_read_b64_tr_b16 v[82:83], v84 offset:53120
	s_waitcnt lgkmcnt(0)
	v_mfma_f32_32x32x16_bf16 v[16:31], v[80:83], v[64:67], v[16:31]
	ds_read_b64_tr_b16 v[80:81], v84 offset:37056
	ds_read_b64_tr_b16 v[82:83], v84 offset:39360
	s_waitcnt lgkmcnt(0)
	v_mfma_f32_32x32x16_bf16 v[0:15], v[80:83], v[76:79], v[0:15]
	ds_read_b64_tr_b16 v[80:81], v84 offset:41664
	ds_read_b64_tr_b16 v[82:83], v84 offset:43968
	s_waitcnt lgkmcnt(0)
	v_mfma_f32_32x32x16_bf16 v[0:15], v[80:83], v[72:75], v[0:15]
	ds_read_b64_tr_b16 v[80:81], v84 offset:46272
	ds_read_b64_tr_b16 v[82:83], v84 offset:48576
	s_waitcnt lgkmcnt(0)
	v_mfma_f32_32x32x16_bf16 v[0:15], v[80:83], v[68:71], v[0:15]
	ds_read_b64_tr_b16 v[80:81], v84 offset:50880
	ds_read_b64_tr_b16 v[82:83], v84 offset:53184
	s_waitcnt lgkmcnt(0)
	v_mfma_f32_32x32x16_bf16 v[0:15], v[80:83], v[64:67], v[0:15]

; #define PG8_STAGE(bufoff, gbase, voff) do { _Pragma("unroll") for (int _i = 0; _i < 2; ++_i) \
;         __builtin_amdgcn_global_load_lds((const unsigned*)((const char*)(gbase) + (voff)[_i]), (PG8_LAS unsigned*)(lds + (bufoff) + ldsw + _i * 8192), 16, 0, 0); } while (0)
; #define PG8_LDA(dst, b, h) do { _Pragma("unroll") for (int m = 0; m < 4; ++m) _Pragma("unroll") for (int k = 0; k < 2; ++k) dst[m][k] = *(const PG8_LAS bf16x8*)(lds + PG8_SA(b, h) + aoff + m * 2048 + k * 1024); } while (0)
; #define PG8_LDB(dst, b, h) do { _Pragma("unroll") for (int n = 0; n < 2; ++n) _Pragma("unroll") for (int k = 0; k < 2; ++k) dst[n][k] = *(const PG8_LAS bf16x8*)(lds + PG8_SB(b, h) + boff + n * 2048 + k * 1024); } while (0)
; #define PG8_MMA(ai, bj, At, Bt) do { __builtin_amdgcn_s_setprio(1); _Pragma("unroll") for (int m = 0; m < 4; ++m) _Pragma("unroll") for (int n = 0; n < 2; ++n) _Pragma("unroll") for (int k = 0; k < 2; ++k) \
;         acc[ai][bj][m][n] = __builtin_amdgcn_mfma_f32_16x16x32_bf16(Bt[n][k], At[m][k], acc[ai][bj][m][n], 0, 0, 0); __builtin_amdgcn_s_setprio(0); } while (0)
; #define PG8_WAIT_V(n) asm volatile("s_waitcnt vmcnt(" #n ")" ::: "memory")
; #define PG8_WAIT_L(n) asm volatile("s_waitcnt lgkmcnt(" #n ")" ::: "memory")
; #define PG8_BAR __builtin_amdgcn_s_barrier()
; #define PG8_SCHED __builtin_amdgcn_sched_barrier(0)
; template <class Epi, class Sched, bool ALIGN_EPI = false, bool SP2 = false>
; __device__ __forceinline__ void gemm_phase(PG8_LAS unsigned char* lds, const Gemm g, const Sched& S, const Epi& E) {
;     ...
;             PG8_LDB(B0, 0, 0); PG8_LDB(B1, 0, 1); PG8_SCHED; PG8_LDA(At, 0, 0); PG8_STAGE(PG8_SA(1, 1), a1 + hstepA, voffA);
;             PG8_WAIT_V(8); PG8_WAIT_L(0); PG8_BAR; PG8_MMA(0, 0, At, B0); PG8_MMA(0, 1, At, B1); PG8_BAR; PG8_SCHED;
;     ...
; #pragma unroll
;         for (int a = 0; a < 2; ++a)
; #pragma unroll
;             for (int b = 0; b < 2; ++b)
; #pragma unroll
;                 for (int m = 0; m < 4; ++m)
; #pragma unroll
;                     for (int n = 0; n < 2; ++n) acc[a][b][m][n] = (f32x4){0.f, 0.f, 0.f, 0.f};
;         cur = nxt; cA = nA; cB = nB; ++ui;
.LBB0_660:
	s_add_u32 s0, s14, 0x80
	s_addc_u32 s1, s15, 0
	s_add_u32 s9, s2, 0x100
	v_mov_b32_e32 v4, 0
	s_addc_u32 s14, s3, 0
	s_mov_b32 s2, 0
	v_mov_b32_e32 v5, v4
	v_mov_b32_e32 v6, v4
	v_mov_b32_e32 v7, v4
	v_mov_b32_e32 v68, v4
	v_mov_b32_e32 v69, v4
	v_mov_b32_e32 v70, v4
	v_mov_b32_e32 v71, v4
	v_mov_b32_e32 v8, v4
	v_mov_b32_e32 v9, v4
	v_mov_b32_e32 v10, v4
	v_mov_b32_e32 v11, v4
	v_mov_b32_e32 v72, v4
	v_mov_b32_e32 v73, v4
	v_mov_b32_e32 v74, v4
	v_mov_b32_e32 v75, v4
	v_mov_b32_e32 v16, v4
	v_mov_b32_e32 v17, v4
	v_mov_b32_e32 v18, v4
	v_mov_b32_e32 v19, v4
	v_mov_b32_e32 v80, v4
	v_mov_b32_e32 v81, v4
	v_mov_b32_e32 v82, v4
	v_mov_b32_e32 v83, v4
	v_mov_b32_e32 v28, v4
	v_mov_b32_e32 v29, v4
	v_mov_b32_e32 v30, v4
	v_mov_b32_e32 v31, v4
	v_mov_b32_e32 v92, v4
	v_mov_b32_e32 v93, v4
	v_mov_b32_e32 v94, v4
	v_mov_b32_e32 v95, v4
	v_mov_b32_e32 v0, v4
	v_mov_b32_e32 v1, v4
	v_mov_b32_e32 v2, v4
	v_mov_b32_e32 v3, v4
	v_mov_b32_e32 v64, v4
	v_mov_b32_e32 v65, v4
	v_mov_b32_e32 v66, v4
	v_mov_b32_e32 v67, v4
	v_mov_b32_e32 v12, v4
	v_mov_b32_e32 v13, v4
	v_mov_b32_e32 v14, v4
	v_mov_b32_e32 v15, v4
	v_mov_b32_e32 v76, v4
	v_mov_b32_e32 v77, v4
	v_mov_b32_e32 v78, v4
	v_mov_b32_e32 v79, v4
	v_mov_b32_e32 v20, v4
	v_mov_b32_e32 v21, v4
	v_mov_b32_e32 v22, v4
	v_mov_b32_e32 v23, v4
	v_mov_b32_e32 v84, v4
	v_mov_b32_e32 v85, v4
	v_mov_b32_e32 v86, v4
	v_mov_b32_e32 v87, v4
	v_mov_b32_e32 v24, v4
	v_mov_b32_e32 v25, v4
	v_mov_b32_e32 v26, v4
	v_mov_b32_e32 v27, v4
	v_mov_b32_e32 v88, v4
	v_mov_b32_e32 v89, v4
	v_mov_b32_e32 v90, v4
	v_mov_b32_e32 v91, v4
	v_mov_b32_e32 v36, v4
	v_mov_b32_e32 v37, v4
	v_mov_b32_e32 v38, v4
	v_mov_b32_e32 v39, v4
	v_mov_b32_e32 v102, v4
	v_mov_b32_e32 v103, v4
	v_mov_b32_e32 v104, v4
	v_mov_b32_e32 v105, v4
	v_mov_b32_e32 v40, v4
	v_mov_b32_e32 v41, v4
	v_mov_b32_e32 v42, v4
	v_mov_b32_e32 v43, v4
	v_mov_b32_e32 v106, v4
	v_mov_b32_e32 v107, v4
	v_mov_b32_e32 v108, v4
	v_mov_b32_e32 v109, v4
	v_mov_b32_e32 v48, v4
	v_mov_b32_e32 v49, v4
	v_mov_b32_e32 v50, v4
	v_mov_b32_e32 v51, v4
	v_mov_b32_e32 v114, v4
	v_mov_b32_e32 v115, v4
	v_mov_b32_e32 v116, v4
	v_mov_b32_e32 v117, v4
	v_mov_b32_e32 v60, v4
	v_mov_b32_e32 v61, v4
	v_mov_b32_e32 v62, v4
	v_mov_b32_e32 v63, v4
	v_mov_b32_e32 v126, v4
	v_mov_b32_e32 v127, v4
	v_mov_b32_e32 v128, v4
	v_mov_b32_e32 v129, v4
	v_mov_b32_e32 v32, v4
	v_mov_b32_e32 v33, v4
	v_mov_b32_e32 v34, v4
	v_mov_b32_e32 v35, v4
	v_mov_b32_e32 v98, v4
	v_mov_b32_e32 v99, v4
	v_mov_b32_e32 v100, v4
	v_mov_b32_e32 v101, v4
	v_mov_b32_e32 v44, v4
	v_mov_b32_e32 v45, v4
	v_mov_b32_e32 v46, v4
	v_mov_b32_e32 v47, v4
	v_mov_b32_e32 v110, v4
	v_mov_b32_e32 v111, v4
	v_mov_b32_e32 v112, v4
	v_mov_b32_e32 v113, v4
	v_mov_b32_e32 v52, v4
	v_mov_b32_e32 v53, v4
	v_mov_b32_e32 v54, v4
	v_mov_b32_e32 v55, v4
	v_mov_b32_e32 v118, v4
	v_mov_b32_e32 v119, v4
	v_mov_b32_e32 v120, v4
	v_mov_b32_e32 v121, v4
	v_mov_b32_e32 v56, v4
	v_mov_b32_e32 v57, v4
	v_mov_b32_e32 v58, v4
	v_mov_b32_e32 v59, v4
	v_mov_b32_e32 v122, v4
	v_mov_b32_e32 v123, v4
	v_mov_b32_e32 v124, v4
	v_mov_b32_e32 v125, v4
	v_add_u32_e32 v234, s60, v150
	v_add_u32_e32 v235, s60, v154
	s_waitcnt vmcnt(0)
.LBB0_661:
	s_add_i32 s15, s2, 2
	s_add_u32 s6, s0, 0x80
	s_mov_b32 s7, 0x10000
	s_addc_u32 s3, s1, 0
	s_addk_i32 s7, 0x100
	s_waitcnt lgkmcnt(0)
	v_add_u32_e32 v96, s7, v157
	ds_read_b128 v[130:133], v96
	ds_read_b128 v[134:137], v96 offset:1024
	ds_read_b128 v[138:141], v96 offset:2048
	ds_read_b128 v[142:145], v96 offset:3072
	v_add_u32_e32 v96, s77, v157
	ds_read_b128 v[172:175], v96
	ds_read_b128 v[176:179], v96 offset:1024
	ds_read_b128 v[180:183], v96 offset:2048
	ds_read_b128 v[184:187], v96 offset:3072
	s_cmp_eq_u32 s41, s2
	s_cselect_b32 s2, s24, s6
	s_cselect_b32 s3, s25, s3
	s_cselect_b32 s17, s27, s14
	s_cselect_b32 s16, s26, s9
	s_add_i32 m0, s72, 0xc000
	ds_read_b128 v[188:191], v193
	ds_read_b128 v[194:197], v193 offset:1024
	ds_read_b128 v[198:201], v193 offset:2048
	ds_read_b128 v[202:205], v193 offset:3072
	ds_read_b128 v[206:209], v193 offset:4096
	ds_read_b128 v[210:213], v193 offset:5120
	ds_read_b128 v[214:217], v193 offset:6144
	ds_read_b128 v[228:231], v193 offset:7168
	global_load_lds_dwordx4 v168, s[0:1]
	s_add_i32 m0, s72, 0xe000
	s_nop 0
	global_load_lds_dwordx4 v170, s[0:1]
	s_waitcnt vmcnt(8)
	s_waitcnt lgkmcnt(0)
	s_barrier
	s_setprio 1
	s_waitcnt lgkmcnt(0)
	v_mfma_f32_16x16x32_bf16 v[122:125], v[130:133], v[188:191], v[122:125]
	v_mfma_f32_16x16x32_bf16 v[56:59], v[138:141], v[188:191], v[56:59]
	v_mfma_f32_16x16x32_bf16 v[118:121], v[130:133], v[198:201], v[118:121]
	v_mfma_f32_16x16x32_bf16 v[52:55], v[138:141], v[198:201], v[52:55]
	v_mfma_f32_16x16x32_bf16 v[110:113], v[130:133], v[206:209], v[110:113]
	v_mfma_f32_16x16x32_bf16 v[44:47], v[138:141], v[206:209], v[44:47]
	v_mfma_f32_16x16x32_bf16 v[98:101], v[130:133], v[214:217], v[98:101]
	v_mfma_f32_16x16x32_bf16 v[32:35], v[138:141], v[214:217], v[32:35]
	v_mfma_f32_16x16x32_bf16 v[122:125], v[134:137], v[194:197], v[122:125]
	v_mfma_f32_16x16x32_bf16 v[56:59], v[142:145], v[194:197], v[56:59]
	v_mfma_f32_16x16x32_bf16 v[118:121], v[134:137], v[202:205], v[118:121]
	v_mfma_f32_16x16x32_bf16 v[52:55], v[142:145], v[202:205], v[52:55]
	v_mfma_f32_16x16x32_bf16 v[110:113], v[134:137], v[210:213], v[110:113]
	v_mfma_f32_16x16x32_bf16 v[44:47], v[142:145], v[210:213], v[44:47]
	v_mfma_f32_16x16x32_bf16 v[98:101], v[134:137], v[228:231], v[98:101]
	v_mfma_f32_16x16x32_bf16 v[32:35], v[142:145], v[228:231], v[32:35]
	s_setprio 0
	s_setprio 1
	v_mfma_f32_16x16x32_bf16 v[126:129], v[172:175], v[188:191], v[126:129]
	v_mfma_f32_16x16x32_bf16 v[60:63], v[180:183], v[188:191], v[60:63]
	v_mfma_f32_16x16x32_bf16 v[114:117], v[172:175], v[198:201], v[114:117]
	v_mfma_f32_16x16x32_bf16 v[48:51], v[180:183], v[198:201], v[48:51]
	v_mfma_f32_16x16x32_bf16 v[106:109], v[172:175], v[206:209], v[106:109]
	v_mfma_f32_16x16x32_bf16 v[40:43], v[180:183], v[206:209], v[40:43]
	v_mfma_f32_16x16x32_bf16 v[102:105], v[172:175], v[214:217], v[102:105]
	v_mfma_f32_16x16x32_bf16 v[36:39], v[180:183], v[214:217], v[36:39]
	v_mfma_f32_16x16x32_bf16 v[126:129], v[176:179], v[194:197], v[126:129]
	v_mfma_f32_16x16x32_bf16 v[60:63], v[184:187], v[194:197], v[60:63]
	v_mfma_f32_16x16x32_bf16 v[114:117], v[176:179], v[202:205], v[114:117]
	v_mfma_f32_16x16x32_bf16 v[48:51], v[184:187], v[202:205], v[48:51]
	v_mfma_f32_16x16x32_bf16 v[106:109], v[176:179], v[210:213], v[106:109]
	v_mfma_f32_16x16x32_bf16 v[40:43], v[184:187], v[210:213], v[40:43]
	v_mfma_f32_16x16x32_bf16 v[102:105], v[176:179], v[228:231], v[102:105]
	v_mfma_f32_16x16x32_bf16 v[36:39], v[184:187], v[228:231], v[36:39]
	s_setprio 0
	s_barrier
; #define PG8_STAGE(bufoff, gbase, voff) do { _Pragma("unroll") for (int _i = 0; _i < 2; ++_i) \
;         __builtin_amdgcn_global_load_lds((const unsigned*)((const char*)(gbase) + (voff)[_i]), (PG8_LAS unsigned*)(lds + (bufoff) + ldsw + _i * 8192), 16, 0, 0); } while (0)
; #define PG8_LDA(dst, b, h) do { _Pragma("unroll") for (int m = 0; m < 4; ++m) _Pragma("unroll") for (int k = 0; k < 2; ++k) dst[m][k] = *(const PG8_LAS bf16x8*)(lds + PG8_SA(b, h) + aoff + m * 2048 + k * 1024); } while (0)
; #define PG8_LDB(dst, b, h) do { _Pragma("unroll") for (int n = 0; n < 2; ++n) _Pragma("unroll") for (int k = 0; k < 2; ++k) dst[n][k] = *(const PG8_LAS bf16x8*)(lds + PG8_SB(b, h) + boff + n * 2048 + k * 1024); } while (0)
; #define PG8_MMA(ai, bj, At, Bt) do { __builtin_amdgcn_s_setprio(1); _Pragma("unroll") for (int m = 0; m < 4; ++m) _Pragma("unroll") for (int n = 0; n < 2; ++n) _Pragma("unroll") for (int k = 0; k < 2; ++k) \
;         acc[ai][bj][m][n] = __builtin_amdgcn_mfma_f32_16x16x32_bf16(Bt[n][k], At[m][k], acc[ai][bj][m][n], 0, 0, 0); __builtin_amdgcn_s_setprio(0); } while (0)
; #define PG8_WAIT_V(n) asm volatile("s_waitcnt vmcnt(" #n ")" ::: "memory")
; #define PG8_WAIT_L(n) asm volatile("s_waitcnt lgkmcnt(" #n ")" ::: "memory")
; #define PG8_BAR __builtin_amdgcn_s_barrier()
; #define PG8_SCHED __builtin_amdgcn_sched_barrier(0)
; template <class Epi, class Sched, bool ALIGN_EPI = false, bool SP2 = false>
; __device__ __forceinline__ void gemm_phase(PG8_LAS unsigned char* lds, const Gemm g, const Sched& S, const Epi& E) {
;     ...
;             PG8_LDA(At, 0, 1); PG8_STAGE(PG8_SB(0, 0), b2, voffB); PG8_STAGE(PG8_SB(0, 1), b2 + hstepB, voffB); PG8_STAGE(PG8_SA(0, 0), a2, voffA);
;             PG8_WAIT_V(8); PG8_WAIT_L(0); PG8_BAR; PG8_MMA(1, 0, At, B0); PG8_MMA(1, 1, At, B1); PG8_BAR; PG8_SCHED;
;             PG8_LDB(B0, 1, 0); PG8_LDB(B1, 1, 1); PG8_SCHED; PG8_LDA(At, 1, 0); PG8_STAGE(PG8_SA(0, 1), a2 + hstepA, voffA);
;             PG8_WAIT_V(8); PG8_WAIT_L(0); PG8_BAR; PG8_MMA(0, 0, At, B0); PG8_MMA(0, 1, At, B1); PG8_BAR; PG8_SCHED;
	s_add_i32 s6, s7, s71
	s_mov_b32 m0, s6
	ds_read_b128 v[188:191], v193 offset:16384
	ds_read_b128 v[194:197], v193 offset:17408
	ds_read_b128 v[198:201], v193 offset:18432
	ds_read_b128 v[202:205], v193 offset:19456
	ds_read_b128 v[206:209], v193 offset:20480
	ds_read_b128 v[210:213], v193 offset:21504
	ds_read_b128 v[214:217], v193 offset:22528
	ds_read_b128 v[228:231], v193 offset:23552
	global_load_lds_dwordx4 v150, s[16:17]
	s_add_i32 m0, s6, 0x2000
	s_add_i32 s6, s77, s71
	global_load_lds_dwordx4 v154, s[16:17]
	s_mov_b32 m0, s6
	s_nop 0
	global_load_lds_dwordx4 v234, s[16:17]
	s_add_i32 m0, s6, 0x2000
	s_nop 0
	global_load_lds_dwordx4 v235, s[16:17]
	s_mov_b32 m0, s72
	s_nop 0
	global_load_lds_dwordx4 v148, s[2:3]
	s_mov_b32 m0, s73
	s_nop 0
	global_load_lds_dwordx4 v152, s[2:3]
	s_waitcnt vmcnt(8)
	s_waitcnt lgkmcnt(0)
	s_barrier
	s_setprio 1
	s_waitcnt lgkmcnt(0)
	v_mfma_f32_16x16x32_bf16 v[88:91], v[130:133], v[188:191], v[88:91]
	v_mfma_f32_16x16x32_bf16 v[24:27], v[138:141], v[188:191], v[24:27]
	v_mfma_f32_16x16x32_bf16 v[84:87], v[130:133], v[198:201], v[84:87]
	v_mfma_f32_16x16x32_bf16 v[20:23], v[138:141], v[198:201], v[20:23]
	v_mfma_f32_16x16x32_bf16 v[76:79], v[130:133], v[206:209], v[76:79]
	v_mfma_f32_16x16x32_bf16 v[12:15], v[138:141], v[206:209], v[12:15]
	v_mfma_f32_16x16x32_bf16 v[64:67], v[130:133], v[214:217], v[64:67]
	v_mfma_f32_16x16x32_bf16 v[0:3], v[138:141], v[214:217], v[0:3]
	v_mfma_f32_16x16x32_bf16 v[88:91], v[134:137], v[194:197], v[88:91]
	v_mfma_f32_16x16x32_bf16 v[24:27], v[142:145], v[194:197], v[24:27]
	v_mfma_f32_16x16x32_bf16 v[84:87], v[134:137], v[202:205], v[84:87]
	v_mfma_f32_16x16x32_bf16 v[20:23], v[142:145], v[202:205], v[20:23]
	v_mfma_f32_16x16x32_bf16 v[76:79], v[134:137], v[210:213], v[76:79]
	v_mfma_f32_16x16x32_bf16 v[12:15], v[142:145], v[210:213], v[12:15]
	v_mfma_f32_16x16x32_bf16 v[64:67], v[134:137], v[228:231], v[64:67]
	v_mfma_f32_16x16x32_bf16 v[0:3], v[142:145], v[228:231], v[0:3]
	s_setprio 0
	s_setprio 1
	v_mfma_f32_16x16x32_bf16 v[92:95], v[172:175], v[188:191], v[92:95]
	v_mfma_f32_16x16x32_bf16 v[28:31], v[180:183], v[188:191], v[28:31]
	v_mfma_f32_16x16x32_bf16 v[80:83], v[172:175], v[198:201], v[80:83]
	v_mfma_f32_16x16x32_bf16 v[16:19], v[180:183], v[198:201], v[16:19]
	v_mfma_f32_16x16x32_bf16 v[72:75], v[172:175], v[206:209], v[72:75]
	v_mfma_f32_16x16x32_bf16 v[8:11], v[180:183], v[206:209], v[8:11]
	v_mfma_f32_16x16x32_bf16 v[68:71], v[172:175], v[214:217], v[68:71]
	v_mfma_f32_16x16x32_bf16 v[4:7], v[180:183], v[214:217], v[4:7]
	v_mfma_f32_16x16x32_bf16 v[92:95], v[176:179], v[194:197], v[92:95]
	v_mfma_f32_16x16x32_bf16 v[28:31], v[184:187], v[194:197], v[28:31]
	v_mfma_f32_16x16x32_bf16 v[80:83], v[176:179], v[202:205], v[80:83]
	v_mfma_f32_16x16x32_bf16 v[16:19], v[184:187], v[202:205], v[16:19]
	v_mfma_f32_16x16x32_bf16 v[72:75], v[176:179], v[210:213], v[72:75]
	v_mfma_f32_16x16x32_bf16 v[8:11], v[184:187], v[210:213], v[8:11]
	v_mfma_f32_16x16x32_bf16 v[68:71], v[176:179], v[228:231], v[68:71]
	v_mfma_f32_16x16x32_bf16 v[4:7], v[184:187], v[228:231], v[4:7]
	s_setprio 0
	s_barrier
	v_add_u32_e32 v96, s33, v157
	ds_read_b128 v[130:133], v96
	ds_read_b128 v[134:137], v96 offset:1024
	ds_read_b128 v[138:141], v96 offset:2048
	ds_read_b128 v[142:145], v96 offset:3072
	v_add_u32_e32 v96, s12, v157
	ds_read_b128 v[172:175], v96
	ds_read_b128 v[176:179], v96 offset:1024
	ds_read_b128 v[180:183], v96 offset:2048
	ds_read_b128 v[184:187], v96 offset:3072
	s_mov_b32 m0, s62
	ds_read_b128 v[188:191], v193 offset:32768
	ds_read_b128 v[194:197], v193 offset:33792
	ds_read_b128 v[198:201], v193 offset:34816
	ds_read_b128 v[202:205], v193 offset:35840
	ds_read_b128 v[206:209], v193 offset:36864
	ds_read_b128 v[210:213], v193 offset:37888
	ds_read_b128 v[214:217], v193 offset:38912
	ds_read_b128 v[228:231], v193 offset:39936
	global_load_lds_dwordx4 v168, s[2:3]
	s_mov_b32 m0, s63
	s_nop 0
	global_load_lds_dwordx4 v170, s[2:3]
	s_waitcnt vmcnt(8)
	s_waitcnt lgkmcnt(0)
	s_barrier
; #define PG8_STAGE(bufoff, gbase, voff) do { _Pragma("unroll") for (int _i = 0; _i < 2; ++_i) \
;         __builtin_amdgcn_global_load_lds((const unsigned*)((const char*)(gbase) + (voff)[_i]), (PG8_LAS unsigned*)(lds + (bufoff) + ldsw + _i * 8192), 16, 0, 0); } while (0)
; #define PG8_LDA(dst, b, h) do { _Pragma("unroll") for (int m = 0; m < 4; ++m) _Pragma("unroll") for (int k = 0; k < 2; ++k) dst[m][k] = *(const PG8_LAS bf16x8*)(lds + PG8_SA(b, h) + aoff + m * 2048 + k * 1024); } while (0)
; #define PG8_MMA(ai, bj, At, Bt) do { __builtin_amdgcn_s_setprio(1); _Pragma("unroll") for (int m = 0; m < 4; ++m) _Pragma("unroll") for (int n = 0; n < 2; ++n) _Pragma("unroll") for (int k = 0; k < 2; ++k) \
;         acc[ai][bj][m][n] = __builtin_amdgcn_mfma_f32_16x16x32_bf16(Bt[n][k], At[m][k], acc[ai][bj][m][n], 0, 0, 0); __builtin_amdgcn_s_setprio(0); } while (0)
; #define PG8_WAIT_V(n) asm volatile("s_waitcnt vmcnt(" #n ")" ::: "memory")
; #define PG8_WAIT_L(n) asm volatile("s_waitcnt lgkmcnt(" #n ")" ::: "memory")
; #define PG8_BAR __builtin_amdgcn_s_barrier()
; #define PG8_SCHED __builtin_amdgcn_sched_barrier(0)
; template <class Epi, class Sched, bool ALIGN_EPI = false, bool SP2 = false>
; __device__ __forceinline__ void gemm_phase(PG8_LAS unsigned char* lds, const Gemm g, const Sched& S, const Epi& E) {
;     ...
;         for (int t = 0; t < nt; t += 2) {
;     ...
;             PG8_LDA(At, 1, 1); PG8_STAGE(PG8_SB(1, 0), b3, voffB); PG8_STAGE(PG8_SB(1, 1), b3 + hstepB, voffB); PG8_STAGE(PG8_SA(1, 0), a3, voffA);
;             PG8_WAIT_V(8); PG8_WAIT_L(0); PG8_BAR; PG8_MMA(1, 0, At, B0); PG8_MMA(1, 1, At, B1); PG8_BAR; PG8_SCHED;
	s_setprio 1
	s_waitcnt lgkmcnt(0)
	v_mfma_f32_16x16x32_bf16 v[122:125], v[130:133], v[188:191], v[122:125]
	v_mfma_f32_16x16x32_bf16 v[56:59], v[138:141], v[188:191], v[56:59]
	v_mfma_f32_16x16x32_bf16 v[118:121], v[130:133], v[198:201], v[118:121]
	v_mfma_f32_16x16x32_bf16 v[52:55], v[138:141], v[198:201], v[52:55]
	v_mfma_f32_16x16x32_bf16 v[110:113], v[130:133], v[206:209], v[110:113]
	v_mfma_f32_16x16x32_bf16 v[44:47], v[138:141], v[206:209], v[44:47]
	v_mfma_f32_16x16x32_bf16 v[98:101], v[130:133], v[214:217], v[98:101]
	v_mfma_f32_16x16x32_bf16 v[32:35], v[138:141], v[214:217], v[32:35]
	v_mfma_f32_16x16x32_bf16 v[122:125], v[134:137], v[194:197], v[122:125]
	v_mfma_f32_16x16x32_bf16 v[56:59], v[142:145], v[194:197], v[56:59]
	v_mfma_f32_16x16x32_bf16 v[118:121], v[134:137], v[202:205], v[118:121]
	v_mfma_f32_16x16x32_bf16 v[52:55], v[142:145], v[202:205], v[52:55]
	v_mfma_f32_16x16x32_bf16 v[110:113], v[134:137], v[210:213], v[110:113]
	v_mfma_f32_16x16x32_bf16 v[44:47], v[142:145], v[210:213], v[44:47]
	v_mfma_f32_16x16x32_bf16 v[98:101], v[134:137], v[228:231], v[98:101]
	v_mfma_f32_16x16x32_bf16 v[32:35], v[142:145], v[228:231], v[32:35]
	s_setprio 0
	s_setprio 1
	v_mfma_f32_16x16x32_bf16 v[126:129], v[172:175], v[188:191], v[126:129]
	v_mfma_f32_16x16x32_bf16 v[60:63], v[180:183], v[188:191], v[60:63]
	v_mfma_f32_16x16x32_bf16 v[114:117], v[172:175], v[198:201], v[114:117]
	v_mfma_f32_16x16x32_bf16 v[48:51], v[180:183], v[198:201], v[48:51]
	v_mfma_f32_16x16x32_bf16 v[106:109], v[172:175], v[206:209], v[106:109]
	v_mfma_f32_16x16x32_bf16 v[40:43], v[180:183], v[206:209], v[40:43]
	v_mfma_f32_16x16x32_bf16 v[102:105], v[172:175], v[214:217], v[102:105]
	v_mfma_f32_16x16x32_bf16 v[36:39], v[180:183], v[214:217], v[36:39]
	v_mfma_f32_16x16x32_bf16 v[126:129], v[176:179], v[194:197], v[126:129]
	v_mfma_f32_16x16x32_bf16 v[60:63], v[184:187], v[194:197], v[60:63]
	v_mfma_f32_16x16x32_bf16 v[114:117], v[176:179], v[202:205], v[114:117]
	v_mfma_f32_16x16x32_bf16 v[48:51], v[184:187], v[202:205], v[48:51]
	v_mfma_f32_16x16x32_bf16 v[106:109], v[176:179], v[210:213], v[106:109]
	v_mfma_f32_16x16x32_bf16 v[40:43], v[184:187], v[210:213], v[40:43]
	v_mfma_f32_16x16x32_bf16 v[102:105], v[176:179], v[228:231], v[102:105]
	v_mfma_f32_16x16x32_bf16 v[36:39], v[184:187], v[228:231], v[36:39]
	s_setprio 0
	s_barrier
	s_add_i32 s6, s33, s71
	s_mov_b32 m0, s6
	s_add_u32 s16, s16, 0x80
	s_addc_u32 s17, s17, 0
	s_add_u32 s2, s2, 0x80
	s_addc_u32 s3, s3, 0
	ds_read_b128 v[188:191], v193 offset:49152
	ds_read_b128 v[194:197], v193 offset:50176
	ds_read_b128 v[198:201], v193 offset:51200
	ds_read_b128 v[202:205], v193 offset:52224
	ds_read_b128 v[206:209], v193 offset:53248
	ds_read_b128 v[210:213], v193 offset:54272
	ds_read_b128 v[214:217], v193 offset:55296
	ds_read_b128 v[228:231], v193 offset:56320
	global_load_lds_dwordx4 v150, s[16:17]
	s_add_i32 m0, s6, 0x2000
	s_add_i32 s6, s12, s71
	global_load_lds_dwordx4 v154, s[16:17]
	s_mov_b32 m0, s6
	s_nop 0
	global_load_lds_dwordx4 v234, s[16:17]
	s_add_i32 m0, s6, 0x2000
	s_nop 0
	global_load_lds_dwordx4 v235, s[16:17]
	s_mov_b32 m0, s20
	s_nop 0
	global_load_lds_dwordx4 v148, s[2:3]
	s_mov_b32 m0, s21
	s_nop 0
	global_load_lds_dwordx4 v152, s[2:3]
	s_waitcnt vmcnt(8)
	s_waitcnt lgkmcnt(0)
	s_barrier
	s_setprio 1
	s_waitcnt lgkmcnt(0)
	v_mfma_f32_16x16x32_bf16 v[88:91], v[130:133], v[188:191], v[88:91]
	v_mfma_f32_16x16x32_bf16 v[24:27], v[138:141], v[188:191], v[24:27]
	v_mfma_f32_16x16x32_bf16 v[84:87], v[130:133], v[198:201], v[84:87]
	v_mfma_f32_16x16x32_bf16 v[20:23], v[138:141], v[198:201], v[20:23]
	v_mfma_f32_16x16x32_bf16 v[76:79], v[130:133], v[206:209], v[76:79]
	v_mfma_f32_16x16x32_bf16 v[12:15], v[138:141], v[206:209], v[12:15]
	v_mfma_f32_16x16x32_bf16 v[64:67], v[130:133], v[214:217], v[64:67]
	v_mfma_f32_16x16x32_bf16 v[0:3], v[138:141], v[214:217], v[0:3]
	v_mfma_f32_16x16x32_bf16 v[88:91], v[134:137], v[194:197], v[88:91]
	v_mfma_f32_16x16x32_bf16 v[24:27], v[142:145], v[194:197], v[24:27]
	v_mfma_f32_16x16x32_bf16 v[84:87], v[134:137], v[202:205], v[84:87]
	v_mfma_f32_16x16x32_bf16 v[20:23], v[142:145], v[202:205], v[20:23]
	v_mfma_f32_16x16x32_bf16 v[76:79], v[134:137], v[210:213], v[76:79]
	v_mfma_f32_16x16x32_bf16 v[12:15], v[142:145], v[210:213], v[12:15]
	v_mfma_f32_16x16x32_bf16 v[64:67], v[134:137], v[228:231], v[64:67]
	v_mfma_f32_16x16x32_bf16 v[0:3], v[142:145], v[228:231], v[0:3]
	s_setprio 0
	s_setprio 1
	v_mfma_f32_16x16x32_bf16 v[92:95], v[172:175], v[188:191], v[92:95]
	v_mfma_f32_16x16x32_bf16 v[28:31], v[180:183], v[188:191], v[28:31]
	v_mfma_f32_16x16x32_bf16 v[80:83], v[172:175], v[198:201], v[80:83]
	v_mfma_f32_16x16x32_bf16 v[16:19], v[180:183], v[198:201], v[16:19]
	v_mfma_f32_16x16x32_bf16 v[72:75], v[172:175], v[206:209], v[72:75]
	v_mfma_f32_16x16x32_bf16 v[8:11], v[180:183], v[206:209], v[8:11]
	v_mfma_f32_16x16x32_bf16 v[68:71], v[172:175], v[214:217], v[68:71]
	v_mfma_f32_16x16x32_bf16 v[4:7], v[180:183], v[214:217], v[4:7]
	v_mfma_f32_16x16x32_bf16 v[92:95], v[176:179], v[194:197], v[92:95]
	v_mfma_f32_16x16x32_bf16 v[28:31], v[184:187], v[194:197], v[28:31]
	v_mfma_f32_16x16x32_bf16 v[80:83], v[176:179], v[202:205], v[80:83]
	v_mfma_f32_16x16x32_bf16 v[16:19], v[184:187], v[202:205], v[16:19]
	v_mfma_f32_16x16x32_bf16 v[72:75], v[176:179], v[210:213], v[72:75]
	v_mfma_f32_16x16x32_bf16 v[8:11], v[184:187], v[210:213], v[8:11]
	v_mfma_f32_16x16x32_bf16 v[68:71], v[176:179], v[228:231], v[68:71]
	v_mfma_f32_16x16x32_bf16 v[4:7], v[184:187], v[228:231], v[4:7]
	s_setprio 0
	s_barrier
	s_add_u32 s0, s0, 0x100
	s_addc_u32 s1, s1, 0
	s_add_u32 s9, s9, 0x100
	s_addc_u32 s14, s14, 0
	s_cmp_ge_u32 s15, s40
	s_mov_b32 s2, s15
	s_cbranch_scc0 .LBB0_661
	s_and_b64 vcc, exec, s[78:79]
	s_cbranch_vccz .LBB0_664
	s_barrier

; DI void row_decode(int r, int& b, int& s) { if (r < RP) { b = r >> 11; s = r & 2047; } else { const int rr = r - RP; b = 16 + (rr >> 4); s = rr & 15; } }
; DI void phase_norm(ArgsP AP, int n, bool dry) {
;     ...
;         const int r0 = (grp < RP / 16) ? grp * 16 : RP + (grp - RP / 16); const int nrows = (grp < RP / 16) ? 16 : 1; int b, s0; row_decode(r0, b, s0);
;         f32x4 cgv[4], gam[4], shv[4];
; #pragma unroll
;         for (int j = 0; j < 4; ++j) { const int c = lane * 4 + 256 * j;
;             if (has_prev) cgv[j] = *(const f32x4*)(mod + ((size_t)lp * 24 + b) * 6144 + gate_idx * 1024 + c) * *(const f32x4*)(ng + (lp * 4 + gpost_idx) * 1024 + c);
;             if (has_next) { const float* mb = mod + ((size_t)ln * 24 + b) * 6144; gam[j] = *(const f32x4*)(ng + (ln * 4 + gpre_idx) * 1024 + c) * (*(const f32x4*)(mb + scale_idx * 1024 + c) + 1.f); shv[j] = *(const f32x4*)(mb + shift_idx * 1024 + c); } }
.LBB0_1073:
	s_movk_i32 s2, 0x800
	v_lshlrev_b32_e32 v64, 4, v136
	v_add_u32_e32 v65, 0x7800, v136
	v_cmp_gt_i32_e64 s[48:49], s2, v136
	s_movk_i32 s2, 0x7fff
	v_lshlrev_b32_e32 v96, 2, v80
	v_cndmask_b32_e64 v94, v65, v64, s[48:49]
	v_add_u32_e32 v64, 0xffff8000, v94
	v_cmp_lt_i32_e64 s[46:47], s2, v94
	v_lshrrev_b32_e32 v65, 4, v64
	s_mov_b32 s2, 0x8000
	v_add_u32_e32 v65, 16, v65
	v_ashrrev_i32_e32 v66, 11, v94
	v_cmp_gt_i32_e32 vcc, s2, v94
	s_nop 1
	v_cndmask_b32_e32 v65, v65, v66, vcc
	v_add_u32_e32 v68, s8, v65
	v_mov_b64_e32 v[66:67], s[24:25]
	v_mad_i64_i32 v[68:69], s[2:3], v68, s96, v[66:67]
	v_cndmask_b32_e64 v66, 0, 1, s[18:19]
	v_cmp_ne_u32_e64 s[42:43], 1, v66
	v_add_u32_e32 v65, s9, v65
	v_mov_b64_e32 v[66:67], s[16:17]
	v_mad_i64_i32 v[66:67], s[2:3], v65, s96, v[66:67]
	s_mov_b32 s31, s61
	v_cndmask_b32_e64 v65, 0, 1, s[20:21]
	v_lshl_add_u64 v[70:71], v[66:67], 0, s[60:61]
	v_cmp_ne_u32_e64 s[44:45], 1, v65
	v_lshl_add_u64 v[66:67], v[66:67], 0, s[30:31]
	s_andn2_b64 vcc, exec, s[18:19]
	s_cbranch_vccnz .Lnorm_ld_next
	v_lshl_add_u64 v[176:177], v[68:69], 0, v[96:97]
	global_load_dwordx4 v[20:23], v[90:91], off
	global_load_dwordx4 v[140:143], v[176:177], off
	global_load_dwordx4 v[36:39], v[90:91], off offset:1024
	global_load_dwordx4 v[148:151], v[176:177], off offset:1024
	global_load_dwordx4 v[40:43], v[90:91], off offset:2048
	global_load_dwordx4 v[156:159], v[176:177], off offset:2048
	global_load_dwordx4 v[44:47], v[90:91], off offset:3072
	global_load_dwordx4 v[168:171], v[176:177], off offset:3072
.Lnorm_ld_next:
	s_andn2_b64 vcc, exec, s[20:21]
	s_cbranch_vccnz .Lnorm_ld_done
	v_lshl_add_u64 v[178:179], v[70:71], 0, v[96:97]
	v_lshl_add_u64 v[180:181], v[66:67], 0, v[96:97]
	global_load_dwordx4 v[24:27], v[178:179], off
	global_load_dwordx4 v[144:147], v[92:93], off
	global_load_dwordx4 v[32:35], v[180:181], off
	global_load_dwordx4 v[12:15], v[178:179], off offset:1024
	global_load_dwordx4 v[152:155], v[92:93], off offset:1024
	global_load_dwordx4 v[28:31], v[180:181], off offset:1024
	global_load_dwordx4 v[4:7], v[178:179], off offset:2048
	global_load_dwordx4 v[160:163], v[92:93], off offset:2048
	global_load_dwordx4 v[16:19], v[180:181], off offset:2048
	global_load_dwordx4 v[0:3], v[178:179], off offset:3072
	global_load_dwordx4 v[172:175], v[92:93], off offset:3072
	global_load_dwordx4 v[8:11], v[180:181], off offset:3072
.Lnorm_ld_done:
	s_and_saveexec_b64 s[2:3], s[46:47]
	s_xor_b64 s[2:3], exec, s[2:3]
	s_cbranch_execnz .LBB0_1143

; #define NORM_LDX(rowoff) do { if (n == 0) xn[j] = *(const f32x4*)(xsrc + (size_t)(rowoff) * DM + lane * 4 + 256 * j); \
;             else xr[j] = __builtin_nontemporal_load((const u32x2*)(X + (size_t)(r0 + (rowoff)) * DM + lane * 4 + 256 * j)); } while (0)
; DI void phase_norm(ArgsP AP, int n, bool dry) {
;     ...
;         for (int j = 0; j < 4; ++j) { const int c = lane * 4 + 256 * j;
;             if (has_prev) cgv[j] = *(const f32x4*)(mod + ((size_t)lp * 24 + b) * 6144 + gate_idx * 1024 + c) * *(const f32x4*)(ng + (lp * 4 + gpost_idx) * 1024 + c);
;             if (has_next) { const float* mb = mod + ((size_t)ln * 24 + b) * 6144; gam[j] = *(const f32x4*)(ng + (ln * 4 + gpre_idx) * 1024 + c) * (*(const f32x4*)(mb + scale_idx * 1024 + c) + 1.f); shv[j] = *(const f32x4*)(mb + shift_idx * 1024 + c); } }
;         const float* xsrc = (r0 < RP) ? AP->in[0] + (size_t)r0 * DM : AP->in[1] + (size_t)(r0 - RP) * DM;
;         f32x4 xn[4]; u32x2 xr[4], mn[4];
;     ...
; #pragma unroll
;         for (int j = 0; j < 4; ++j) { NORM_LDX(0); if (has_prev) mn[j] = __builtin_nontemporal_load((const u32x2*)(H + (size_t)r0 * DM + lane * 4 + 256 * j)); }
;         for (int i = 0; i < nrows; ++i) {
.LBB0_1107:
	v_lshl_add_u64 v[64:65], v[66:67], 0, v[86:87]
	v_lshl_add_u64 v[114:115], v[64:65], 0, s[94:95]
	v_mov_b64_e32 v[66:67], v[62:63]
	v_mov_b64_e32 v[70:71], v[58:59]
	v_mov_b64_e32 v[74:75], v[54:55]
	v_mov_b64_e32 v[78:79], v[50:51]
	v_cndmask_b32_e64 v95, 1, 16, s[48:49]
	s_mov_b32 s31, 0
	s_mov_b64 s[34:35], 0
	s_waitcnt vmcnt(0)
	s_and_b64 vcc, exec, s[42:43]
	s_cbranch_vccnz .Lnorm_m_next
	v_pk_mul_f32 v[22:23], v[142:143], v[22:23]
	v_pk_mul_f32 v[20:21], v[140:141], v[20:21]
	v_pk_mul_f32 v[38:39], v[150:151], v[38:39]
	v_pk_mul_f32 v[36:37], v[148:149], v[36:37]
	v_pk_mul_f32 v[42:43], v[158:159], v[42:43]
	v_pk_mul_f32 v[40:41], v[156:157], v[40:41]
	v_pk_mul_f32 v[46:47], v[170:171], v[46:47]
	v_pk_mul_f32 v[44:45], v[168:169], v[44:45]
.Lnorm_m_next:
	s_and_b64 vcc, exec, s[44:45]
	s_cbranch_vccnz .Lnorm_m_done
	v_pk_add_f32 v[26:27], v[26:27], 1.0 op_sel_hi:[1,0]
	v_pk_add_f32 v[24:25], v[24:25], 1.0 op_sel_hi:[1,0]
	v_pk_mul_f32 v[26:27], v[146:147], v[26:27]
	v_pk_mul_f32 v[24:25], v[144:145], v[24:25]
	v_pk_add_f32 v[14:15], v[14:15], 1.0 op_sel_hi:[1,0]
	v_pk_add_f32 v[12:13], v[12:13], 1.0 op_sel_hi:[1,0]
	v_pk_mul_f32 v[14:15], v[154:155], v[14:15]
	v_pk_mul_f32 v[12:13], v[152:153], v[12:13]
	v_pk_add_f32 v[6:7], v[6:7], 1.0 op_sel_hi:[1,0]
	v_pk_add_f32 v[4:5], v[4:5], 1.0 op_sel_hi:[1,0]
	v_pk_mul_f32 v[6:7], v[162:163], v[6:7]
	v_pk_mul_f32 v[4:5], v[160:161], v[4:5]
	v_pk_add_f32 v[2:3], v[2:3], 1.0 op_sel_hi:[1,0]
	v_pk_add_f32 v[0:1], v[0:1], 1.0 op_sel_hi:[1,0]
	v_pk_mul_f32 v[2:3], v[174:175], v[2:3]
	v_pk_mul_f32 v[0:1], v[172:173], v[0:1]
.Lnorm_m_done:
	v_mov_b64_e32 v[130:131], v[98:99]
	v_mov_b64_e32 v[116:117], v[112:113]
	v_mov_b64_e32 v[118:119], v[110:111]
	v_mov_b64_e32 v[120:121], v[108:109]
	v_mov_b64_e32 v[64:65], v[60:61]
	v_mov_b64_e32 v[68:69], v[56:57]
	v_mov_b64_e32 v[72:73], v[52:53]
	v_mov_b64_e32 v[76:77], v[48:49]
	s_branch .LBB0_1109
